# in-proj and FFN-up tile order with 4-row-panel groups (4 x 8 blocks per XCD round instead of 8 x 4), matching column permutation 15*pn+20 mod 44
# speedup vs baseline: 1.0088x; 1.0088x over previous
.LBB0_134:
	s_load_dwordx16 s[4:19], s[0:1], 0x70
	s_cmp_lt_i32 s44, 2
	s_cselect_b64 s[0:1], -1, 0
	s_cmp_gt_i32 s45, 1
	s_cselect_b64 s[2:3], -1, 0
	s_waitcnt lgkmcnt(0)
	v_writelane_b32 v254, s4, 28
	s_and_b64 s[0:1], s[0:1], s[2:3]
	s_andn2_b64 vcc, exec, s[0:1]
	v_writelane_b32 v254, s5, 29
	v_writelane_b32 v254, s6, 30
	v_writelane_b32 v254, s7, 31
	v_writelane_b32 v254, s8, 32
	v_writelane_b32 v254, s9, 33
	v_writelane_b32 v254, s10, 34
	v_writelane_b32 v254, s11, 35
	v_writelane_b32 v254, s12, 36
	v_writelane_b32 v254, s13, 37
	v_writelane_b32 v254, s14, 38
	v_writelane_b32 v254, s15, 39
	v_writelane_b32 v254, s16, 40
	v_writelane_b32 v254, s17, 41
	v_writelane_b32 v254, s18, 42
	v_writelane_b32 v254, s19, 43
	v_writelane_b32 v254, s84, 44
	s_mov_b64 s[0:1], s[44:45]
	s_mov_b32 s2, s46
	v_writelane_b32 v254, s85, 45
	v_writelane_b32 v254, s86, 46
	v_writelane_b32 v254, s87, 47
	v_writelane_b32 v254, s88, 48
	v_writelane_b32 v254, s89, 49
	v_writelane_b32 v254, s90, 50
	v_writelane_b32 v254, s91, 51
	v_writelane_b32 v254, s0, 52
	s_nop 1
	v_writelane_b32 v254, s1, 53
	v_writelane_b32 v254, s2, 54
	v_writelane_b32 v254, s3, 55
	v_writelane_b32 v254, s43, 56
	s_cbranch_vccnz .LBB0_671
	s_cmpk_lt_i32 s43, 0x5ac
	s_cselect_b64 s[2:3], -1, 0
	s_cmpk_gt_i32 s43, 0x5ab
	v_readfirstlane_b32 s8, v0
	s_cbranch_scc1 .LBB0_137
	s_ashr_i32 s0, s43, 31
	s_lshr_b32 s0, s0, 29
	s_add_i32 s0, s43, s0
	s_and_b32 s1, s0, -8
	s_sub_i32 s1, s43, s1
	s_mul_i32 s5, s1, 0xb5
	s_add_i32 s5, s5, 4
	s_ashr_i32 s0, s0, 3
	s_mul_i32 s4, s1, 0xb6
	s_cmp_lt_i32 s1, 4
	s_cselect_b32 s1, s4, s5
	s_add_i32 s1, s1, s0
	s_mul_hi_i32 s0, s1, 0x2e8ba2e9
	s_lshr_b32 s4, s0, 31
	s_ashr_i32 s0, s0, 5
	s_add_i32 s0, s0, s4
	s_lshl_b32 s4, s0, 2
	s_sub_i32 s5, 33, s4
	s_mulk_i32 s0, 0xb0
	s_min_u32 s5, s5, 4
	s_sub_i32 s6, s1, s0
	s_sext_i32_i16 s0, s6
	v_cvt_f32_ubyte0_e32 v2, s5
	v_cvt_f32_i32_e32 v1, s0
	v_rcp_iflag_f32_e32 v3, v2
	s_ashr_i32 s0, s0, 30
	s_or_b32 s7, s0, 1
	v_mul_f32_e32 v3, v1, v3
	v_trunc_f32_e32 v3, v3
	v_fma_f32 v1, -v3, v2, v1
	v_cvt_i32_f32_e32 v3, v3
	v_cmp_ge_f32_e64 s[0:1], |v1|, v2
	s_and_b64 s[0:1], s[0:1], exec
	s_cselect_b32 s0, s7, 0
	v_readfirstlane_b32 s1, v3
	s_add_i32 s1, s1, s0
	s_sext_i32_i16 s0, s1
	s_mul_i32 s1, s1, s5
	s_sub_i32 s1, s6, s1
	s_sext_i32_i16 s1, s1
	s_add_i32 s4, s4, s1
	s_mul_i32 s0, s0, 15
	s_add_i32 s0, s0, 20
	s_mul_i32 s1, s0, 0x5d2
	s_lshr_b32 s1, s1, 16
	s_mul_i32 s1, s1, 44
	s_sub_i32 s0, s0, s1

.LBB0_148:
	s_ashr_i32 s1, s1, 3
	s_add_i32 s1, s22, s1
	s_mul_hi_i32 s5, s1, 0x2e8ba2e9
	s_lshr_b32 s20, s5, 31
	s_ashr_i32 s5, s5, 5
	s_add_i32 s5, s5, s20
	s_lshl_b32 s21, s5, 2
	s_sub_i32 s20, 33, s21
	s_min_i32 s22, s20, 4
	s_abs_i32 s20, s22
	v_cvt_f32_u32_e32 v2, s20
	s_sub_i32 s24, 0, s20
	s_mulk_i32 s5, 0xb0
	s_sub_i32 s1, s1, s5
	v_rcp_iflag_f32_e32 v2, v2
	s_abs_i32 s5, s1
	s_xor_b32 s23, s1, s22
	s_ashr_i32 s23, s23, 31
	v_mul_f32_e32 v2, 0x4f7ffffe, v2
	v_cvt_u32_f32_e32 v2, v2
	s_nop 0
	v_readfirstlane_b32 s25, v2
	s_mul_i32 s24, s24, s25
	s_mul_hi_u32 s24, s25, s24
	s_add_i32 s25, s25, s24
	s_mul_hi_u32 s24, s5, s25
	s_mul_i32 s25, s24, s20
	s_sub_i32 s5, s5, s25
	s_add_i32 s26, s24, 1
	s_sub_i32 s25, s5, s20
	s_cmp_ge_u32 s5, s20
	s_cselect_b32 s24, s26, s24
	s_cselect_b32 s5, s25, s5
	s_add_i32 s25, s24, 1
	s_cmp_ge_u32 s5, s20
	s_cselect_b32 s5, s25, s24
	s_xor_b32 s5, s5, s23
	s_sub_i32 s20, s5, s23
	s_mul_i32 s5, s20, s22
	s_sub_i32 s1, s1, s5
	s_add_i32 s22, s21, s1
	s_mul_i32 s20, s20, 15
	s_add_i32 s20, s20, 20
	s_mul_i32 s5, s20, 0x5d2
	s_lshr_b32 s5, s5, 16
	s_mul_i32 s5, s5, 44
	s_sub_i32 s20, s20, s5

.LBB0_1121:
	s_cmp_lt_i32 s44, 7
	s_cselect_b64 s[0:1], -1, 0
	s_cmp_gt_i32 s45, 6
	s_cselect_b64 s[2:3], -1, 0
	s_and_b64 s[0:1], s[0:1], s[2:3]
	s_andn2_b64 vcc, exec, s[0:1]
	s_cbranch_vccnz .LBB0_1204
	v_lshlrev_b32_e32 v1, 2, v0
	s_cmpk_gt_i32 s43, 0x5ab
	v_readfirstlane_b32 s1, v0
	s_cbranch_scc1 .LBB0_1142
	v_lshrrev_b32_e32 v4, 1, v0
	v_and_b32_e32 v13, 24, v4
	v_lshrrev_b32_e32 v4, 5, v0
	s_add_u32 s26, s68, 0x2a000000
	v_lshlrev_b32_e32 v2, 4, v0
	v_and_b32_e32 v3, 32, v0
	v_and_b32_e32 v4, 4, v4
	v_bfe_u32 v5, v0, 2, 2
	s_addc_u32 s27, s69, 0
	v_bfe_u32 v12, v0, 2, 4
	v_bitop3_b32 v10, v2, v3, 48 bitop3:0x6c
	v_and_b32_e32 v11, 64, v0
	v_or3_b32 v4, v4, v5, v13
	v_lshrrev_b32_e32 v5, 3, v0
	v_or_b32_e32 v14, 0x2000, v2
	s_add_u32 s28, s68, 0x4600000
	v_or_b32_e32 v3, v10, v11
	v_and_or_b32 v6, v5, 48, v12
	v_and_or_b32 v5, v5, 32, v4
	v_lshrrev_b32_e32 v2, 7, v14
	s_movk_i32 s0, 0x70
	s_addc_u32 s29, s69, 0
	v_lshl_or_b32 v132, v5, 12, v3
	v_and_or_b32 v5, v2, s0, v12
	s_movk_i32 s0, 0x60
	s_ashr_i32 s31, s43, 31
	v_and_or_b32 v2, v2, s0, v4
	s_lshr_b32 s0, s31, 29
	s_add_i32 s0, s43, s0
	s_and_b32 s2, s0, -8
	s_sub_i32 s2, s43, s2
	s_lshr_b32 s6, s1, 6
	s_mul_i32 s4, s2, 0xb5
	s_lshr_b32 s8, s1, 8
	s_lshl_b32 s30, s6, 10
	s_add_i32 s4, s4, 4
	s_ashr_i32 s0, s0, 3
	s_mul_i32 s3, s2, 0xb6
	s_cmp_lt_i32 s2, 4
	s_cselect_b32 s2, s3, s4
	s_add_i32 s2, s2, s0
	s_mul_hi_i32 s0, s2, 0x2e8ba2e9
	s_lshr_b32 s3, s0, 31
	s_ashr_i32 s0, s0, 5
	s_add_i32 s0, s0, s3
	s_lshl_b32 s4, s0, 2
	s_sub_i32 s3, 33, s4
	s_mulk_i32 s0, 0xb0
	s_min_u32 s5, s3, 4
	s_sub_i32 s7, s2, s0
	v_lshl_or_b32 v134, v5, 12, v3
	s_sext_i32_i16 s0, s7
	v_cvt_f32_ubyte0_e32 v5, s5
	v_lshl_or_b32 v130, v6, 12, v3
	v_cvt_f32_i32_e32 v4, s0
	v_rcp_iflag_f32_e32 v6, v5
	v_lshl_or_b32 v136, v2, 12, v3
	s_ashr_i32 s0, s0, 30
	s_or_b32 s0, s0, 1
	v_mul_f32_e32 v2, v4, v6
	v_trunc_f32_e32 v2, v2
	v_fma_f32 v3, -v2, v5, v4
	v_cvt_i32_f32_e32 v2, v2
	v_cmp_ge_f32_e64 s[2:3], |v3|, v5
	s_and_b64 s[2:3], s[2:3], exec
	s_cselect_b32 s0, s0, 0
	v_readfirstlane_b32 s2, v2
	s_add_i32 s0, s2, s0
	s_mul_i32 s2, s0, s5
	s_sub_i32 s2, s7, s2
	s_sext_i32_i16 s2, s2
	s_add_i32 s18, s4, s2
	s_ashr_i32 s19, s18, 31
	s_bfe_i64 s[4:5], s[0:1], 0x100000
	s_lshl_b64 s[2:3], s[18:19], 20
	s_lshl_b64 s[4:5], s[4:5], 20
	s_add_u32 s22, s28, s4
	s_addc_u32 s23, s29, s5
	s_add_i32 s19, s30, 0
	s_add_i32 m0, s19, 0x10000
	v_mov_b32_e32 v133, 0
	v_lshrrev_b32_e32 v240, 6, v0
	v_bfe_u32 v241, v0, 3, 3
	v_and_b32_e32 v242, 7, v0
	v_lshrrev_b32_e32 v243, 1, v241
	v_and_b32_e32 v244, 1, v240
	v_lshl_or_b32 v243, v244, 2, v243
	v_xor_b32_e32 v242, v242, v243
	v_lshlrev_b32_e32 v242, 4, v242
	v_lshl_add_u32 v245, v240, 3, v241
	v_lshrrev_b32_e32 v246, 2, v240
	v_lshlrev_b32_e32 v246, 5, v246
	v_lshl_add_u32 v246, v244, 4, v246
	v_lshrrev_b32_e32 v247, 2, v241
	v_lshl_add_u32 v246, v247, 3, v246
	v_bfe_u32 v247, v240, 1, 1
	v_lshl_add_u32 v246, v247, 2, v246
	v_and_b32_e32 v247, 3, v241
	v_add_u32_e32 v246, v246, v247
	v_lshl_add_u32 v130, v245, 12, v242
	v_lshl_add_u32 v132, v246, 12, v242
	v_add_u32_e32 v134, 0x40000, v130
	v_add_u32_e32 v136, 0x40000, v132
	global_load_lds_dwordx4 v132, s[22:23]
	s_add_i32 m0, s19, 0x12000
	s_add_u32 s4, s22, 0x80000
	global_load_lds_dwordx4 v136, s[22:23]
	s_addc_u32 s5, s23, 0
	s_add_i32 m0, s19, 0x14000
	v_mov_b32_e32 v137, v133
	global_load_lds_dwordx4 v132, s[4:5]
	s_add_i32 m0, s19, 0x16000
	s_add_u32 s20, s26, s2
	s_addc_u32 s21, s27, s3
	s_add_i32 s33, s19, 0x2000
	global_load_lds_dwordx4 v136, s[4:5]
	s_mov_b32 m0, s19
	s_add_u32 s2, s20, 0x80000
	global_load_lds_dwordx4 v130, s[20:21]
	s_mov_b32 m0, s33
	s_addc_u32 s3, s21, 0
	s_add_i32 s34, s19, 0x4000
	global_load_lds_dwordx4 v134, s[20:21]
	s_mov_b32 m0, s34
	s_add_i32 s35, s19, 0x6000
	global_load_lds_dwordx4 v130, s[2:3]
	s_mov_b32 m0, s35
	v_mov_b32_e32 v131, v133
	global_load_lds_dwordx4 v134, s[2:3]
	v_mov_b32_e32 v135, v133
	s_cmp_eq_u32 s8, 1
	s_mov_b32 s36, 0
	v_lshl_add_u64 v[8:9], s[22:23], 0, v[132:133]
	v_lshl_add_u64 v[6:7], s[22:23], 0, v[136:137]
	v_lshl_add_u64 v[2:3], s[20:21], 0, v[130:131]
	s_cselect_b64 s[2:3], -1, 0
	s_cmp_lg_u32 s8, 1
	v_lshl_add_u64 v[4:5], s[20:21], 0, v[134:135]
	s_cbranch_scc1 .LBB0_1125
	s_barrier

.LBB0_1133:
	s_ashr_i32 s10, s12, 3
	s_add_i32 s10, s14, s10
	s_mul_hi_i32 s11, s10, 0x2e8ba2e9
	s_lshr_b32 s12, s11, 31
	s_ashr_i32 s11, s11, 5
	s_add_i32 s11, s11, s12
	s_lshl_b32 s12, s11, 2
	s_sub_i32 s13, 33, s12
	s_min_i32 s13, s13, 4
	s_abs_i32 s14, s13
	v_cvt_f32_u32_e32 v2, s14
	s_sub_i32 s16, 0, s14
	s_mulk_i32 s11, 0xb0
	s_sub_i32 s11, s10, s11
	v_rcp_iflag_f32_e32 v2, v2
	s_abs_i32 s10, s11
	s_xor_b32 s15, s11, s13
	s_ashr_i32 s15, s15, 31
	v_mul_f32_e32 v2, 0x4f7ffffe, v2
	v_cvt_u32_f32_e32 v2, v2
	s_nop 0
	v_readfirstlane_b32 s17, v2
	s_mul_i32 s16, s16, s17
	s_mul_hi_u32 s16, s17, s16
	s_add_i32 s17, s17, s16
	s_mul_hi_u32 s16, s10, s17
	s_mul_i32 s17, s16, s14
	s_sub_i32 s10, s10, s17
	s_add_i32 s24, s16, 1
	s_sub_i32 s17, s10, s14
	s_cmp_ge_u32 s10, s14
	s_cselect_b32 s16, s24, s16
	s_cselect_b32 s10, s17, s10
	s_add_i32 s17, s16, 1
	s_cmp_ge_u32 s10, s14
	s_cselect_b32 s10, s17, s16
	s_xor_b32 s10, s10, s15
	s_sub_i32 s10, s10, s15
	s_mul_i32 s13, s10, s13
	s_sub_i32 s11, s11, s13
	s_add_i32 s12, s12, s11
